# cmp top-k bit search specialised by candidate row count (1 or 2 of 4 ballot rows when cur<66 / cur<130), on top of the hand-written out-proj epilogue
# speedup vs baseline: 1.0172x; 1.0172x over previous
; __device__ __forceinline__ void phase_cmp(const Params& p, LAS unsigned char* lds, const bf16_t* Z, const float* G, const bf16_t* KC, const bf16_t* ACCW, float* ACC, int* IDX, ...
;     ...
;             for (int qi = wid; qi < 64; qi += 8) {
;                 const int cur = qb;
;                 unsigned v[4]; bool ok[4];
; #pragma unroll
;                 for (int i = 0; i < 4; ++i) { const int j = lane + 64 * i; ok[i] = (j >= 1) && (j <= cur - 2); v[i] = ok[i] ? PS[j * 64 + qi] : 0u; }
;                 unsigned T = 0u;
;     ...
; #pragma unroll
;                     for (int i = 0; i < 4; ++i) cnt += __builtin_popcountll(__ballot(ok[i] && v[i] >= trial));
;                     if (cnt >= 13) T = trial; }
.LBB0_433:
	s_waitcnt lgkmcnt(0)
	s_cmp_lt_u32 s91, 66
	s_cbranch_scc1 .Ltk_r1
	s_cmpk_lt_u32 s91, 0x82
	s_cbranch_scc1 .Ltk_r2
	s_or_b32 s23, s96, 0x40000000
	v_cmp_le_u32_e64 s[20:21], s23, v2
	v_cmp_le_u32_e64 s[98:99], s23, v5
	v_cmp_le_u32_e64 s[100:101], s23, v4
	s_bcnt1_i32_b64 s24, s[20:21]
	v_cmp_le_u32_e64 s[20:21], s23, v0
	s_bcnt1_i32_b64 s25, s[98:99]
	s_add_i32 s24, s24, s25
	s_bcnt1_i32_b64 s25, s[100:101]
	s_add_i32 s24, s24, s25
	s_bcnt1_i32_b64 s25, s[20:21]
	s_add_i32 s24, s24, s25
	s_cmp_gt_u32 s24, 12
	s_cselect_b32 s96, s23, s96
	s_or_b32 s23, s96, 0x20000000
	v_cmp_le_u32_e64 s[20:21], s23, v2
	v_cmp_le_u32_e64 s[98:99], s23, v5
	v_cmp_le_u32_e64 s[100:101], s23, v4
	s_bcnt1_i32_b64 s24, s[20:21]
	v_cmp_le_u32_e64 s[20:21], s23, v0
	s_bcnt1_i32_b64 s25, s[98:99]
	s_add_i32 s24, s24, s25
	s_bcnt1_i32_b64 s25, s[100:101]
	s_add_i32 s24, s24, s25
	s_bcnt1_i32_b64 s25, s[20:21]
	s_add_i32 s24, s24, s25
	s_cmp_gt_u32 s24, 12
	s_cselect_b32 s96, s23, s96
	s_or_b32 s23, s96, 0x10000000
	v_cmp_le_u32_e64 s[20:21], s23, v2
	v_cmp_le_u32_e64 s[98:99], s23, v5
	v_cmp_le_u32_e64 s[100:101], s23, v4
	s_bcnt1_i32_b64 s24, s[20:21]
	v_cmp_le_u32_e64 s[20:21], s23, v0
	s_bcnt1_i32_b64 s25, s[98:99]
	s_add_i32 s24, s24, s25
	s_bcnt1_i32_b64 s25, s[100:101]
	s_add_i32 s24, s24, s25
	s_bcnt1_i32_b64 s25, s[20:21]
	s_add_i32 s24, s24, s25
	s_cmp_gt_u32 s24, 12
	s_cselect_b32 s96, s23, s96
	s_or_b32 s23, s96, 0x8000000
	v_cmp_le_u32_e64 s[20:21], s23, v2
	v_cmp_le_u32_e64 s[98:99], s23, v5
	v_cmp_le_u32_e64 s[100:101], s23, v4
	s_bcnt1_i32_b64 s24, s[20:21]
	v_cmp_le_u32_e64 s[20:21], s23, v0
	s_bcnt1_i32_b64 s25, s[98:99]
	s_add_i32 s24, s24, s25
	s_bcnt1_i32_b64 s25, s[100:101]
	s_add_i32 s24, s24, s25
	s_bcnt1_i32_b64 s25, s[20:21]
	s_add_i32 s24, s24, s25
	s_cmp_gt_u32 s24, 12
	s_cselect_b32 s96, s23, s96
	s_or_b32 s23, s96, 0x4000000
	v_cmp_le_u32_e64 s[20:21], s23, v2
	v_cmp_le_u32_e64 s[98:99], s23, v5
	v_cmp_le_u32_e64 s[100:101], s23, v4
	s_bcnt1_i32_b64 s24, s[20:21]
	v_cmp_le_u32_e64 s[20:21], s23, v0
	s_bcnt1_i32_b64 s25, s[98:99]
	s_add_i32 s24, s24, s25
	s_bcnt1_i32_b64 s25, s[100:101]
	s_add_i32 s24, s24, s25
	s_bcnt1_i32_b64 s25, s[20:21]
	s_add_i32 s24, s24, s25
	s_cmp_gt_u32 s24, 12
	s_cselect_b32 s96, s23, s96
	s_or_b32 s23, s96, 0x2000000
	v_cmp_le_u32_e64 s[20:21], s23, v2
	v_cmp_le_u32_e64 s[98:99], s23, v5
	v_cmp_le_u32_e64 s[100:101], s23, v4
	s_bcnt1_i32_b64 s24, s[20:21]
	v_cmp_le_u32_e64 s[20:21], s23, v0
	s_bcnt1_i32_b64 s25, s[98:99]
	s_add_i32 s24, s24, s25
	s_bcnt1_i32_b64 s25, s[100:101]
	s_add_i32 s24, s24, s25
	s_bcnt1_i32_b64 s25, s[20:21]
	s_add_i32 s24, s24, s25
	s_cmp_gt_u32 s24, 12
	s_cselect_b32 s96, s23, s96
	s_or_b32 s23, s96, 0x1000000
	v_cmp_le_u32_e64 s[20:21], s23, v2
	v_cmp_le_u32_e64 s[98:99], s23, v5
	v_cmp_le_u32_e64 s[100:101], s23, v4
	s_bcnt1_i32_b64 s24, s[20:21]
	v_cmp_le_u32_e64 s[20:21], s23, v0
	s_bcnt1_i32_b64 s25, s[98:99]
	s_add_i32 s24, s24, s25
	s_bcnt1_i32_b64 s25, s[100:101]
	s_add_i32 s24, s24, s25
	s_bcnt1_i32_b64 s25, s[20:21]
	s_add_i32 s24, s24, s25
	s_cmp_gt_u32 s24, 12
	s_cselect_b32 s96, s23, s96
	s_or_b32 s23, s96, 0x800000
	v_cmp_le_u32_e64 s[20:21], s23, v2
	v_cmp_le_u32_e64 s[98:99], s23, v5
	v_cmp_le_u32_e64 s[100:101], s23, v4
	s_bcnt1_i32_b64 s24, s[20:21]
	v_cmp_le_u32_e64 s[20:21], s23, v0
	s_bcnt1_i32_b64 s25, s[98:99]
	s_add_i32 s24, s24, s25
	s_bcnt1_i32_b64 s25, s[100:101]
	s_add_i32 s24, s24, s25
	s_bcnt1_i32_b64 s25, s[20:21]
	s_add_i32 s24, s24, s25
	s_cmp_gt_u32 s24, 12
	s_cselect_b32 s96, s23, s96
	s_or_b32 s23, s96, 0x400000
	v_cmp_le_u32_e64 s[20:21], s23, v2
	v_cmp_le_u32_e64 s[98:99], s23, v5
	v_cmp_le_u32_e64 s[100:101], s23, v4
	s_bcnt1_i32_b64 s24, s[20:21]
	v_cmp_le_u32_e64 s[20:21], s23, v0
	s_bcnt1_i32_b64 s25, s[98:99]
	s_add_i32 s24, s24, s25
	s_bcnt1_i32_b64 s25, s[100:101]
	s_add_i32 s24, s24, s25
	s_bcnt1_i32_b64 s25, s[20:21]
	s_add_i32 s24, s24, s25
	s_cmp_gt_u32 s24, 12
	s_cselect_b32 s96, s23, s96
	s_or_b32 s23, s96, 0x200000
	v_cmp_le_u32_e64 s[20:21], s23, v2
	v_cmp_le_u32_e64 s[98:99], s23, v5
	v_cmp_le_u32_e64 s[100:101], s23, v4
	s_bcnt1_i32_b64 s24, s[20:21]
	v_cmp_le_u32_e64 s[20:21], s23, v0
	s_bcnt1_i32_b64 s25, s[98:99]
	s_add_i32 s24, s24, s25
	s_bcnt1_i32_b64 s25, s[100:101]
	s_add_i32 s24, s24, s25
	s_bcnt1_i32_b64 s25, s[20:21]
	s_add_i32 s24, s24, s25
	s_cmp_gt_u32 s24, 12
	s_cselect_b32 s96, s23, s96
	s_or_b32 s23, s96, 0x100000
	v_cmp_le_u32_e64 s[20:21], s23, v2
	v_cmp_le_u32_e64 s[98:99], s23, v5
	v_cmp_le_u32_e64 s[100:101], s23, v4
	s_bcnt1_i32_b64 s24, s[20:21]
	v_cmp_le_u32_e64 s[20:21], s23, v0
	s_bcnt1_i32_b64 s25, s[98:99]
	s_add_i32 s24, s24, s25
	s_bcnt1_i32_b64 s25, s[100:101]
	s_add_i32 s24, s24, s25
	s_bcnt1_i32_b64 s25, s[20:21]
	s_add_i32 s24, s24, s25
	s_cmp_gt_u32 s24, 12
	s_cselect_b32 s96, s23, s96
	s_or_b32 s23, s96, 0x80000
	v_cmp_le_u32_e64 s[20:21], s23, v2
	v_cmp_le_u32_e64 s[98:99], s23, v5
	v_cmp_le_u32_e64 s[100:101], s23, v4
	s_bcnt1_i32_b64 s24, s[20:21]
	v_cmp_le_u32_e64 s[20:21], s23, v0
	s_bcnt1_i32_b64 s25, s[98:99]
	s_add_i32 s24, s24, s25
	s_bcnt1_i32_b64 s25, s[100:101]
	s_add_i32 s24, s24, s25
	s_bcnt1_i32_b64 s25, s[20:21]
	s_add_i32 s24, s24, s25
	s_cmp_gt_u32 s24, 12
	s_cselect_b32 s96, s23, s96
	s_or_b32 s23, s96, 0x40000
	v_cmp_le_u32_e64 s[20:21], s23, v2
	v_cmp_le_u32_e64 s[98:99], s23, v5
	v_cmp_le_u32_e64 s[100:101], s23, v4
	s_bcnt1_i32_b64 s24, s[20:21]
	v_cmp_le_u32_e64 s[20:21], s23, v0
	s_bcnt1_i32_b64 s25, s[98:99]
	s_add_i32 s24, s24, s25
	s_bcnt1_i32_b64 s25, s[100:101]
	s_add_i32 s24, s24, s25
	s_bcnt1_i32_b64 s25, s[20:21]
	s_add_i32 s24, s24, s25
; __device__ __forceinline__ void phase_cmp(const Params& p, LAS unsigned char* lds, const bf16_t* Z, const float* G, const bf16_t* KC, const bf16_t* ACCW, float* ACC, int* IDX, ...
;     ...
; #pragma unroll
;                     for (int i = 0; i < 4; ++i) cnt += __builtin_popcountll(__ballot(ok[i] && v[i] >= trial));
;                     if (cnt >= 13) T = trial; }
	s_cmp_gt_u32 s24, 12
	s_cselect_b32 s96, s23, s96
	s_or_b32 s23, s96, 0x20000
	v_cmp_le_u32_e64 s[20:21], s23, v2
	v_cmp_le_u32_e64 s[98:99], s23, v5
	v_cmp_le_u32_e64 s[100:101], s23, v4
	s_bcnt1_i32_b64 s24, s[20:21]
	v_cmp_le_u32_e64 s[20:21], s23, v0
	s_bcnt1_i32_b64 s25, s[98:99]
	s_add_i32 s24, s24, s25
	s_bcnt1_i32_b64 s25, s[100:101]
	s_add_i32 s24, s24, s25
	s_bcnt1_i32_b64 s25, s[20:21]
	s_add_i32 s24, s24, s25
	s_cmp_gt_u32 s24, 12
	s_cselect_b32 s96, s23, s96
	s_or_b32 s23, s96, 0x10000
	v_cmp_le_u32_e64 s[20:21], s23, v2
	v_cmp_le_u32_e64 s[98:99], s23, v5
	v_cmp_le_u32_e64 s[100:101], s23, v4
	s_bcnt1_i32_b64 s24, s[20:21]
	v_cmp_le_u32_e64 s[20:21], s23, v0
	s_bcnt1_i32_b64 s25, s[98:99]
	s_add_i32 s24, s24, s25
	s_bcnt1_i32_b64 s25, s[100:101]
	s_add_i32 s24, s24, s25
	s_bcnt1_i32_b64 s25, s[20:21]
	s_add_i32 s24, s24, s25
	s_cmp_gt_u32 s24, 12
	s_cselect_b32 s96, s23, s96
	s_or_b32 s23, s96, 0x8000
	v_cmp_le_u32_e64 s[20:21], s23, v2
	v_cmp_le_u32_e64 s[98:99], s23, v5
	v_cmp_le_u32_e64 s[100:101], s23, v4
	s_bcnt1_i32_b64 s24, s[20:21]
	v_cmp_le_u32_e64 s[20:21], s23, v0
	s_bcnt1_i32_b64 s25, s[98:99]
	s_add_i32 s24, s24, s25
	s_bcnt1_i32_b64 s25, s[100:101]
	s_add_i32 s24, s24, s25
	s_bcnt1_i32_b64 s25, s[20:21]
	s_add_i32 s24, s24, s25
	s_cmp_gt_u32 s24, 12
	s_cselect_b32 s96, s23, s96
	s_or_b32 s23, s96, 0x4000
	v_cmp_le_u32_e64 s[20:21], s23, v2
	v_cmp_le_u32_e64 s[98:99], s23, v5
	v_cmp_le_u32_e64 s[100:101], s23, v4
	s_bcnt1_i32_b64 s24, s[20:21]
	v_cmp_le_u32_e64 s[20:21], s23, v0
	s_bcnt1_i32_b64 s25, s[98:99]
	s_add_i32 s24, s24, s25
	s_bcnt1_i32_b64 s25, s[100:101]
	s_add_i32 s24, s24, s25
	s_bcnt1_i32_b64 s25, s[20:21]
	s_add_i32 s24, s24, s25
	s_cmp_gt_u32 s24, 12
	s_cselect_b32 s96, s23, s96
	s_or_b32 s23, s96, 0x2000
	v_cmp_le_u32_e64 s[20:21], s23, v2
	v_cmp_le_u32_e64 s[98:99], s23, v5
	v_cmp_le_u32_e64 s[100:101], s23, v4
	s_bcnt1_i32_b64 s24, s[20:21]
	v_cmp_le_u32_e64 s[20:21], s23, v0
	s_bcnt1_i32_b64 s25, s[98:99]
	s_add_i32 s24, s24, s25
	s_bcnt1_i32_b64 s25, s[100:101]
	s_add_i32 s24, s24, s25
	s_bcnt1_i32_b64 s25, s[20:21]
	s_add_i32 s24, s24, s25
	s_cmp_gt_u32 s24, 12
	s_cselect_b32 s96, s23, s96
	s_or_b32 s23, s96, 0x1000
	v_cmp_le_u32_e64 s[20:21], s23, v2
	v_cmp_le_u32_e64 s[98:99], s23, v5
	v_cmp_le_u32_e64 s[100:101], s23, v4
	s_bcnt1_i32_b64 s24, s[20:21]
	v_cmp_le_u32_e64 s[20:21], s23, v0
	s_bcnt1_i32_b64 s25, s[98:99]
	s_add_i32 s24, s24, s25
	s_bcnt1_i32_b64 s25, s[100:101]
	s_add_i32 s24, s24, s25
	s_bcnt1_i32_b64 s25, s[20:21]
	s_add_i32 s24, s24, s25
	s_cmp_gt_u32 s24, 12
	s_cselect_b32 s96, s23, s96
	s_or_b32 s23, s96, 0x800
	v_cmp_le_u32_e64 s[20:21], s23, v2
	v_cmp_le_u32_e64 s[98:99], s23, v5
	v_cmp_le_u32_e64 s[100:101], s23, v4
	s_bcnt1_i32_b64 s24, s[20:21]
	v_cmp_le_u32_e64 s[20:21], s23, v0
	s_bcnt1_i32_b64 s25, s[98:99]
	s_add_i32 s24, s24, s25
	s_bcnt1_i32_b64 s25, s[100:101]
	s_add_i32 s24, s24, s25
	s_bcnt1_i32_b64 s25, s[20:21]
	s_add_i32 s24, s24, s25
	s_cmp_gt_u32 s24, 12
	s_cselect_b32 s96, s23, s96
	s_or_b32 s23, s96, 0x400
	v_cmp_le_u32_e64 s[20:21], s23, v2
	v_cmp_le_u32_e64 s[98:99], s23, v5
	v_cmp_le_u32_e64 s[100:101], s23, v4
	s_bcnt1_i32_b64 s24, s[20:21]
	v_cmp_le_u32_e64 s[20:21], s23, v0
	s_bcnt1_i32_b64 s25, s[98:99]
	s_add_i32 s24, s24, s25
	s_bcnt1_i32_b64 s25, s[100:101]
	s_add_i32 s24, s24, s25
	s_bcnt1_i32_b64 s25, s[20:21]
	s_add_i32 s24, s24, s25
	s_cmp_gt_u32 s24, 12
	s_cselect_b32 s96, s23, s96
	s_or_b32 s23, s96, 0x200
	v_cmp_le_u32_e64 s[20:21], s23, v2
	v_cmp_le_u32_e64 s[98:99], s23, v5
	v_cmp_le_u32_e64 s[100:101], s23, v4
	s_bcnt1_i32_b64 s24, s[20:21]
	v_cmp_le_u32_e64 s[20:21], s23, v0
	s_bcnt1_i32_b64 s25, s[98:99]
	s_add_i32 s24, s24, s25
	s_bcnt1_i32_b64 s25, s[100:101]
	s_add_i32 s24, s24, s25
	s_bcnt1_i32_b64 s25, s[20:21]
	s_add_i32 s24, s24, s25
	s_cmp_gt_u32 s24, 12
	s_cselect_b32 s96, s23, s96
	s_or_b32 s23, s96, 0x100
	v_cmp_le_u32_e64 s[20:21], s23, v2
	v_cmp_le_u32_e64 s[98:99], s23, v5
	v_cmp_le_u32_e64 s[100:101], s23, v4
	s_bcnt1_i32_b64 s24, s[20:21]
	v_cmp_le_u32_e64 s[20:21], s23, v0
	s_bcnt1_i32_b64 s25, s[98:99]
	s_add_i32 s24, s24, s25
	s_bcnt1_i32_b64 s25, s[100:101]
	s_add_i32 s24, s24, s25
	s_bcnt1_i32_b64 s25, s[20:21]
	s_add_i32 s24, s24, s25
	s_cmp_gt_u32 s24, 12
	s_cselect_b32 s96, s23, s96
	s_or_b32 s23, s96, 0x80
	v_cmp_le_u32_e64 s[20:21], s23, v2
	v_cmp_le_u32_e64 s[98:99], s23, v5
	v_cmp_le_u32_e64 s[100:101], s23, v4
	s_bcnt1_i32_b64 s24, s[20:21]
	v_cmp_le_u32_e64 s[20:21], s23, v0
	s_bcnt1_i32_b64 s25, s[98:99]
	s_add_i32 s24, s24, s25
	s_bcnt1_i32_b64 s25, s[100:101]
	s_add_i32 s24, s24, s25
	s_bcnt1_i32_b64 s25, s[20:21]
	s_add_i32 s24, s24, s25
	s_cmp_gt_u32 s24, 12
	s_cselect_b32 s96, s23, s96
	s_or_b32 s23, s96, 64
	v_cmp_le_u32_e64 s[20:21], s23, v2
	v_cmp_le_u32_e64 s[98:99], s23, v5
	v_cmp_le_u32_e64 s[100:101], s23, v4
	s_bcnt1_i32_b64 s24, s[20:21]
	v_cmp_le_u32_e64 s[20:21], s23, v0
	s_bcnt1_i32_b64 s25, s[98:99]
	s_add_i32 s24, s24, s25
	s_bcnt1_i32_b64 s25, s[100:101]
	s_add_i32 s24, s24, s25
	s_bcnt1_i32_b64 s25, s[20:21]
	s_add_i32 s24, s24, s25
	s_cmp_gt_u32 s24, 12
	s_cselect_b32 s96, s23, s96
	s_or_b32 s23, s96, 32
	v_cmp_le_u32_e64 s[20:21], s23, v2
	v_cmp_le_u32_e64 s[98:99], s23, v5
	v_cmp_le_u32_e64 s[100:101], s23, v4
	s_bcnt1_i32_b64 s24, s[20:21]
	v_cmp_le_u32_e64 s[20:21], s23, v0
	s_bcnt1_i32_b64 s25, s[98:99]
	s_add_i32 s24, s24, s25
	s_bcnt1_i32_b64 s25, s[100:101]
	s_add_i32 s24, s24, s25
	s_bcnt1_i32_b64 s25, s[20:21]
	s_add_i32 s24, s24, s25
	s_cmp_gt_u32 s24, 12
	s_cselect_b32 s96, s23, s96
	s_or_b32 s23, s96, 16
	v_cmp_le_u32_e64 s[20:21], s23, v2
; __device__ __forceinline__ void phase_cmp(const Params& p, LAS unsigned char* lds, const bf16_t* Z, const float* G, const bf16_t* KC, const bf16_t* ACCW, float* ACC, int* IDX, ...
;     ...
; #pragma unroll
;                     for (int i = 0; i < 4; ++i) cnt += __builtin_popcountll(__ballot(ok[i] && v[i] >= trial));
;                     if (cnt >= 13) T = trial; }
	v_cmp_le_u32_e64 s[98:99], s23, v5
	v_cmp_le_u32_e64 s[100:101], s23, v4
	s_bcnt1_i32_b64 s24, s[20:21]
	v_cmp_le_u32_e64 s[20:21], s23, v0
	s_bcnt1_i32_b64 s25, s[98:99]
	s_add_i32 s24, s24, s25
	s_bcnt1_i32_b64 s25, s[100:101]
	s_add_i32 s24, s24, s25
	s_bcnt1_i32_b64 s25, s[20:21]
	s_add_i32 s24, s24, s25
	s_cmp_gt_u32 s24, 12
	s_cselect_b32 s96, s23, s96
	s_or_b32 s23, s96, 8
	v_cmp_le_u32_e64 s[20:21], s23, v2
	v_cmp_le_u32_e64 s[98:99], s23, v5
	v_cmp_le_u32_e64 s[100:101], s23, v4
	s_bcnt1_i32_b64 s24, s[20:21]
	v_cmp_le_u32_e64 s[20:21], s23, v0
	s_bcnt1_i32_b64 s25, s[98:99]
	s_add_i32 s24, s24, s25
	s_bcnt1_i32_b64 s25, s[100:101]
	s_add_i32 s24, s24, s25
	s_bcnt1_i32_b64 s25, s[20:21]
	s_add_i32 s24, s24, s25
	s_cmp_gt_u32 s24, 12
	s_cselect_b32 s96, s23, s96
	s_or_b32 s23, s96, 4
	v_cmp_le_u32_e64 s[20:21], s23, v2
	v_cmp_le_u32_e64 s[98:99], s23, v5
	v_cmp_le_u32_e64 s[100:101], s23, v4
	s_bcnt1_i32_b64 s24, s[20:21]
	v_cmp_le_u32_e64 s[20:21], s23, v0
	s_bcnt1_i32_b64 s25, s[98:99]
	s_add_i32 s24, s24, s25
	s_bcnt1_i32_b64 s25, s[100:101]
	s_add_i32 s24, s24, s25
	s_bcnt1_i32_b64 s25, s[20:21]
	s_add_i32 s24, s24, s25
	s_cmp_gt_u32 s24, 12
	s_cselect_b32 s96, s23, s96
	s_or_b32 s23, s96, 2
	v_cmp_le_u32_e64 s[20:21], s23, v2
	v_cmp_le_u32_e64 s[98:99], s23, v5
	v_cmp_le_u32_e64 s[100:101], s23, v4
	s_bcnt1_i32_b64 s24, s[20:21]
	v_cmp_le_u32_e64 s[20:21], s23, v0
	s_bcnt1_i32_b64 s25, s[98:99]
	s_add_i32 s24, s24, s25
	s_bcnt1_i32_b64 s25, s[100:101]
	s_add_i32 s24, s24, s25
	s_bcnt1_i32_b64 s25, s[20:21]
	s_add_i32 s24, s24, s25
	s_cmp_gt_u32 s24, 12
	s_cselect_b32 s96, s23, s96
	s_or_b32 s23, s96, 1
	v_cmp_le_u32_e64 s[20:21], s23, v2
	v_cmp_le_u32_e64 s[98:99], s23, v5
	v_cmp_le_u32_e64 s[100:101], s23, v4
	s_bcnt1_i32_b64 s24, s[20:21]
	v_cmp_le_u32_e64 s[20:21], s23, v0
	s_bcnt1_i32_b64 s25, s[98:99]
	s_add_i32 s24, s24, s25
	s_bcnt1_i32_b64 s25, s[100:101]
	s_add_i32 s24, s24, s25
	s_bcnt1_i32_b64 s25, s[20:21]
	s_add_i32 s24, s24, s25
	s_cmp_gt_u32 s24, 12
	s_cselect_b32 s96, s23, s96
	s_branch .Ltk_join
.Ltk_r1:
	s_or_b32 s23, s96, 0x40000000
	v_cmp_le_u32_e64 s[20:21], s23, v2
	s_bcnt1_i32_b64 s24, s[20:21]
	s_cmp_gt_u32 s24, 12
	s_cselect_b32 s96, s23, s96
	s_or_b32 s23, s96, 0x20000000
	v_cmp_le_u32_e64 s[20:21], s23, v2
	s_bcnt1_i32_b64 s24, s[20:21]
	s_cmp_gt_u32 s24, 12
	s_cselect_b32 s96, s23, s96
	s_or_b32 s23, s96, 0x10000000
	v_cmp_le_u32_e64 s[20:21], s23, v2
	s_bcnt1_i32_b64 s24, s[20:21]
	s_cmp_gt_u32 s24, 12
	s_cselect_b32 s96, s23, s96
	s_or_b32 s23, s96, 0x8000000
	v_cmp_le_u32_e64 s[20:21], s23, v2
	s_bcnt1_i32_b64 s24, s[20:21]
	s_cmp_gt_u32 s24, 12
	s_cselect_b32 s96, s23, s96
	s_or_b32 s23, s96, 0x4000000
	v_cmp_le_u32_e64 s[20:21], s23, v2
	s_bcnt1_i32_b64 s24, s[20:21]
	s_cmp_gt_u32 s24, 12
	s_cselect_b32 s96, s23, s96
	s_or_b32 s23, s96, 0x2000000
	v_cmp_le_u32_e64 s[20:21], s23, v2
	s_bcnt1_i32_b64 s24, s[20:21]
	s_cmp_gt_u32 s24, 12
	s_cselect_b32 s96, s23, s96
	s_or_b32 s23, s96, 0x1000000
	v_cmp_le_u32_e64 s[20:21], s23, v2
	s_bcnt1_i32_b64 s24, s[20:21]
	s_cmp_gt_u32 s24, 12
	s_cselect_b32 s96, s23, s96
	s_or_b32 s23, s96, 0x800000
	v_cmp_le_u32_e64 s[20:21], s23, v2
	s_bcnt1_i32_b64 s24, s[20:21]
	s_cmp_gt_u32 s24, 12
	s_cselect_b32 s96, s23, s96
	s_or_b32 s23, s96, 0x400000
	v_cmp_le_u32_e64 s[20:21], s23, v2
	s_bcnt1_i32_b64 s24, s[20:21]
	s_cmp_gt_u32 s24, 12
	s_cselect_b32 s96, s23, s96
	s_or_b32 s23, s96, 0x200000
	v_cmp_le_u32_e64 s[20:21], s23, v2
	s_bcnt1_i32_b64 s24, s[20:21]
	s_cmp_gt_u32 s24, 12
	s_cselect_b32 s96, s23, s96
	s_or_b32 s23, s96, 0x100000
	v_cmp_le_u32_e64 s[20:21], s23, v2
	s_bcnt1_i32_b64 s24, s[20:21]
	s_cmp_gt_u32 s24, 12
	s_cselect_b32 s96, s23, s96
	s_or_b32 s23, s96, 0x80000
	v_cmp_le_u32_e64 s[20:21], s23, v2
	s_bcnt1_i32_b64 s24, s[20:21]
	s_cmp_gt_u32 s24, 12
	s_cselect_b32 s96, s23, s96
	s_or_b32 s23, s96, 0x40000
	v_cmp_le_u32_e64 s[20:21], s23, v2
	s_bcnt1_i32_b64 s24, s[20:21]
	s_cmp_gt_u32 s24, 12
	s_cselect_b32 s96, s23, s96
	s_or_b32 s23, s96, 0x20000
	v_cmp_le_u32_e64 s[20:21], s23, v2
	s_bcnt1_i32_b64 s24, s[20:21]
	s_cmp_gt_u32 s24, 12
	s_cselect_b32 s96, s23, s96
	s_or_b32 s23, s96, 0x10000
	v_cmp_le_u32_e64 s[20:21], s23, v2
	s_bcnt1_i32_b64 s24, s[20:21]
	s_cmp_gt_u32 s24, 12
	s_cselect_b32 s96, s23, s96
	s_or_b32 s23, s96, 0x8000
	v_cmp_le_u32_e64 s[20:21], s23, v2
	s_bcnt1_i32_b64 s24, s[20:21]
	s_cmp_gt_u32 s24, 12
	s_cselect_b32 s96, s23, s96
	s_or_b32 s23, s96, 0x4000
	v_cmp_le_u32_e64 s[20:21], s23, v2
	s_bcnt1_i32_b64 s24, s[20:21]
	s_cmp_gt_u32 s24, 12
	s_cselect_b32 s96, s23, s96
	s_or_b32 s23, s96, 0x2000
	v_cmp_le_u32_e64 s[20:21], s23, v2
	s_bcnt1_i32_b64 s24, s[20:21]
	s_cmp_gt_u32 s24, 12
	s_cselect_b32 s96, s23, s96
	s_or_b32 s23, s96, 0x1000
	v_cmp_le_u32_e64 s[20:21], s23, v2
	s_bcnt1_i32_b64 s24, s[20:21]
	s_cmp_gt_u32 s24, 12
	s_cselect_b32 s96, s23, s96
	s_or_b32 s23, s96, 0x800
	v_cmp_le_u32_e64 s[20:21], s23, v2
	s_bcnt1_i32_b64 s24, s[20:21]
	s_cmp_gt_u32 s24, 12
	s_cselect_b32 s96, s23, s96
	s_or_b32 s23, s96, 0x400
	v_cmp_le_u32_e64 s[20:21], s23, v2
	s_bcnt1_i32_b64 s24, s[20:21]
	s_cmp_gt_u32 s24, 12
	s_cselect_b32 s96, s23, s96
	s_or_b32 s23, s96, 0x200
	v_cmp_le_u32_e64 s[20:21], s23, v2
	s_bcnt1_i32_b64 s24, s[20:21]
	s_cmp_gt_u32 s24, 12
	s_cselect_b32 s96, s23, s96
	s_or_b32 s23, s96, 0x100
	v_cmp_le_u32_e64 s[20:21], s23, v2
	s_bcnt1_i32_b64 s24, s[20:21]
	s_cmp_gt_u32 s24, 12
	s_cselect_b32 s96, s23, s96
	s_or_b32 s23, s96, 0x80
	v_cmp_le_u32_e64 s[20:21], s23, v2
	s_bcnt1_i32_b64 s24, s[20:21]
	s_cmp_gt_u32 s24, 12
	s_cselect_b32 s96, s23, s96
	s_or_b32 s23, s96, 64
	v_cmp_le_u32_e64 s[20:21], s23, v2
	s_bcnt1_i32_b64 s24, s[20:21]
	s_cmp_gt_u32 s24, 12
	s_cselect_b32 s96, s23, s96
	s_or_b32 s23, s96, 32
	v_cmp_le_u32_e64 s[20:21], s23, v2
	s_bcnt1_i32_b64 s24, s[20:21]
	s_cmp_gt_u32 s24, 12
	s_cselect_b32 s96, s23, s96
	s_or_b32 s23, s96, 16
	v_cmp_le_u32_e64 s[20:21], s23, v2
	s_bcnt1_i32_b64 s24, s[20:21]
	s_cmp_gt_u32 s24, 12
	s_cselect_b32 s96, s23, s96
	s_or_b32 s23, s96, 8
	v_cmp_le_u32_e64 s[20:21], s23, v2
	s_bcnt1_i32_b64 s24, s[20:21]
	s_cmp_gt_u32 s24, 12
	s_cselect_b32 s96, s23, s96
	s_or_b32 s23, s96, 4
	v_cmp_le_u32_e64 s[20:21], s23, v2
	s_bcnt1_i32_b64 s24, s[20:21]
	s_cmp_gt_u32 s24, 12
	s_cselect_b32 s96, s23, s96
	s_or_b32 s23, s96, 2
	v_cmp_le_u32_e64 s[20:21], s23, v2
	s_bcnt1_i32_b64 s24, s[20:21]
	s_cmp_gt_u32 s24, 12
	s_cselect_b32 s96, s23, s96
	s_or_b32 s23, s96, 1
	v_cmp_le_u32_e64 s[20:21], s23, v2
	s_bcnt1_i32_b64 s24, s[20:21]
	s_cmp_gt_u32 s24, 12
	s_cselect_b32 s96, s23, s96
	s_branch .Ltk_join
; __device__ __forceinline__ void phase_cmp(const Params& p, LAS unsigned char* lds, const bf16_t* Z, const float* G, const bf16_t* KC, const bf16_t* ACCW, float* ACC, int* IDX, ...
;     ...
; #pragma unroll
;                     for (int i = 0; i < 4; ++i) cnt += __builtin_popcountll(__ballot(ok[i] && v[i] >= trial));
;                     if (cnt >= 13) T = trial; }
.Ltk_r2:
	s_or_b32 s23, s96, 0x40000000
	v_cmp_le_u32_e64 s[20:21], s23, v2
	v_cmp_le_u32_e64 s[98:99], s23, v5
	s_bcnt1_i32_b64 s24, s[20:21]
	s_bcnt1_i32_b64 s25, s[98:99]
	s_add_i32 s24, s24, s25
	s_cmp_gt_u32 s24, 12
	s_cselect_b32 s96, s23, s96
	s_or_b32 s23, s96, 0x20000000
	v_cmp_le_u32_e64 s[20:21], s23, v2
	v_cmp_le_u32_e64 s[98:99], s23, v5
	s_bcnt1_i32_b64 s24, s[20:21]
	s_bcnt1_i32_b64 s25, s[98:99]
	s_add_i32 s24, s24, s25
	s_cmp_gt_u32 s24, 12
	s_cselect_b32 s96, s23, s96
	s_or_b32 s23, s96, 0x10000000
	v_cmp_le_u32_e64 s[20:21], s23, v2
	v_cmp_le_u32_e64 s[98:99], s23, v5
	s_bcnt1_i32_b64 s24, s[20:21]
	s_bcnt1_i32_b64 s25, s[98:99]
	s_add_i32 s24, s24, s25
	s_cmp_gt_u32 s24, 12
	s_cselect_b32 s96, s23, s96
	s_or_b32 s23, s96, 0x8000000
	v_cmp_le_u32_e64 s[20:21], s23, v2
	v_cmp_le_u32_e64 s[98:99], s23, v5
	s_bcnt1_i32_b64 s24, s[20:21]
	s_bcnt1_i32_b64 s25, s[98:99]
	s_add_i32 s24, s24, s25
	s_cmp_gt_u32 s24, 12
	s_cselect_b32 s96, s23, s96
	s_or_b32 s23, s96, 0x4000000
	v_cmp_le_u32_e64 s[20:21], s23, v2
	v_cmp_le_u32_e64 s[98:99], s23, v5
	s_bcnt1_i32_b64 s24, s[20:21]
	s_bcnt1_i32_b64 s25, s[98:99]
	s_add_i32 s24, s24, s25
	s_cmp_gt_u32 s24, 12
	s_cselect_b32 s96, s23, s96
	s_or_b32 s23, s96, 0x2000000
	v_cmp_le_u32_e64 s[20:21], s23, v2
	v_cmp_le_u32_e64 s[98:99], s23, v5
	s_bcnt1_i32_b64 s24, s[20:21]
	s_bcnt1_i32_b64 s25, s[98:99]
	s_add_i32 s24, s24, s25
	s_cmp_gt_u32 s24, 12
	s_cselect_b32 s96, s23, s96
	s_or_b32 s23, s96, 0x1000000
	v_cmp_le_u32_e64 s[20:21], s23, v2
	v_cmp_le_u32_e64 s[98:99], s23, v5
	s_bcnt1_i32_b64 s24, s[20:21]
	s_bcnt1_i32_b64 s25, s[98:99]
	s_add_i32 s24, s24, s25
	s_cmp_gt_u32 s24, 12
	s_cselect_b32 s96, s23, s96
	s_or_b32 s23, s96, 0x800000
	v_cmp_le_u32_e64 s[20:21], s23, v2
	v_cmp_le_u32_e64 s[98:99], s23, v5
	s_bcnt1_i32_b64 s24, s[20:21]
	s_bcnt1_i32_b64 s25, s[98:99]
	s_add_i32 s24, s24, s25
	s_cmp_gt_u32 s24, 12
	s_cselect_b32 s96, s23, s96
	s_or_b32 s23, s96, 0x400000
	v_cmp_le_u32_e64 s[20:21], s23, v2
	v_cmp_le_u32_e64 s[98:99], s23, v5
	s_bcnt1_i32_b64 s24, s[20:21]
	s_bcnt1_i32_b64 s25, s[98:99]
	s_add_i32 s24, s24, s25
	s_cmp_gt_u32 s24, 12
	s_cselect_b32 s96, s23, s96
	s_or_b32 s23, s96, 0x200000
	v_cmp_le_u32_e64 s[20:21], s23, v2
	v_cmp_le_u32_e64 s[98:99], s23, v5
	s_bcnt1_i32_b64 s24, s[20:21]
	s_bcnt1_i32_b64 s25, s[98:99]
	s_add_i32 s24, s24, s25
	s_cmp_gt_u32 s24, 12
	s_cselect_b32 s96, s23, s96
	s_or_b32 s23, s96, 0x100000
	v_cmp_le_u32_e64 s[20:21], s23, v2
	v_cmp_le_u32_e64 s[98:99], s23, v5
	s_bcnt1_i32_b64 s24, s[20:21]
	s_bcnt1_i32_b64 s25, s[98:99]
	s_add_i32 s24, s24, s25
	s_cmp_gt_u32 s24, 12
	s_cselect_b32 s96, s23, s96
	s_or_b32 s23, s96, 0x80000
	v_cmp_le_u32_e64 s[20:21], s23, v2
	v_cmp_le_u32_e64 s[98:99], s23, v5
	s_bcnt1_i32_b64 s24, s[20:21]
	s_bcnt1_i32_b64 s25, s[98:99]
	s_add_i32 s24, s24, s25
	s_cmp_gt_u32 s24, 12
	s_cselect_b32 s96, s23, s96
	s_or_b32 s23, s96, 0x40000
	v_cmp_le_u32_e64 s[20:21], s23, v2
	v_cmp_le_u32_e64 s[98:99], s23, v5
	s_bcnt1_i32_b64 s24, s[20:21]
	s_bcnt1_i32_b64 s25, s[98:99]
	s_add_i32 s24, s24, s25
	s_cmp_gt_u32 s24, 12
	s_cselect_b32 s96, s23, s96
	s_or_b32 s23, s96, 0x20000
	v_cmp_le_u32_e64 s[20:21], s23, v2
	v_cmp_le_u32_e64 s[98:99], s23, v5
	s_bcnt1_i32_b64 s24, s[20:21]
	s_bcnt1_i32_b64 s25, s[98:99]
	s_add_i32 s24, s24, s25
	s_cmp_gt_u32 s24, 12
	s_cselect_b32 s96, s23, s96
	s_or_b32 s23, s96, 0x10000
	v_cmp_le_u32_e64 s[20:21], s23, v2
	v_cmp_le_u32_e64 s[98:99], s23, v5
	s_bcnt1_i32_b64 s24, s[20:21]
	s_bcnt1_i32_b64 s25, s[98:99]
	s_add_i32 s24, s24, s25
	s_cmp_gt_u32 s24, 12
	s_cselect_b32 s96, s23, s96
	s_or_b32 s23, s96, 0x8000
	v_cmp_le_u32_e64 s[20:21], s23, v2
	v_cmp_le_u32_e64 s[98:99], s23, v5
	s_bcnt1_i32_b64 s24, s[20:21]
	s_bcnt1_i32_b64 s25, s[98:99]
	s_add_i32 s24, s24, s25
	s_cmp_gt_u32 s24, 12
	s_cselect_b32 s96, s23, s96
	s_or_b32 s23, s96, 0x4000
	v_cmp_le_u32_e64 s[20:21], s23, v2
	v_cmp_le_u32_e64 s[98:99], s23, v5
	s_bcnt1_i32_b64 s24, s[20:21]
	s_bcnt1_i32_b64 s25, s[98:99]
	s_add_i32 s24, s24, s25
	s_cmp_gt_u32 s24, 12
	s_cselect_b32 s96, s23, s96
	s_or_b32 s23, s96, 0x2000
	v_cmp_le_u32_e64 s[20:21], s23, v2
; __device__ __forceinline__ void phase_cmp(const Params& p, LAS unsigned char* lds, const bf16_t* Z, const float* G, const bf16_t* KC, const bf16_t* ACCW, float* ACC, int* IDX, ...
;     ...
; #pragma unroll
;                     for (int i = 0; i < 4; ++i) cnt += __builtin_popcountll(__ballot(ok[i] && v[i] >= trial));
;                     if (cnt >= 13) T = trial; }
;                 int n_gt = 0;
; #pragma unroll
;                 for (int i = 0; i < 4; ++i) n_gt += __builtin_popcountll(__ballot(ok[i] && v[i] > T));
;                 int* dst = IDX + (((size_t)b * SEQ + qb * 64 + qi) * 2 + g) * 16;
;                 if (lane == 0) { dst[0] = 0; dst[1] = cur - 1; dst[2] = cur; }
	v_cmp_le_u32_e64 s[98:99], s23, v5
	s_bcnt1_i32_b64 s24, s[20:21]
	s_bcnt1_i32_b64 s25, s[98:99]
	s_add_i32 s24, s24, s25
	s_cmp_gt_u32 s24, 12
	s_cselect_b32 s96, s23, s96
	s_or_b32 s23, s96, 0x1000
	v_cmp_le_u32_e64 s[20:21], s23, v2
	v_cmp_le_u32_e64 s[98:99], s23, v5
	s_bcnt1_i32_b64 s24, s[20:21]
	s_bcnt1_i32_b64 s25, s[98:99]
	s_add_i32 s24, s24, s25
	s_cmp_gt_u32 s24, 12
	s_cselect_b32 s96, s23, s96
	s_or_b32 s23, s96, 0x800
	v_cmp_le_u32_e64 s[20:21], s23, v2
	v_cmp_le_u32_e64 s[98:99], s23, v5
	s_bcnt1_i32_b64 s24, s[20:21]
	s_bcnt1_i32_b64 s25, s[98:99]
	s_add_i32 s24, s24, s25
	s_cmp_gt_u32 s24, 12
	s_cselect_b32 s96, s23, s96
	s_or_b32 s23, s96, 0x400
	v_cmp_le_u32_e64 s[20:21], s23, v2
	v_cmp_le_u32_e64 s[98:99], s23, v5
	s_bcnt1_i32_b64 s24, s[20:21]
	s_bcnt1_i32_b64 s25, s[98:99]
	s_add_i32 s24, s24, s25
	s_cmp_gt_u32 s24, 12
	s_cselect_b32 s96, s23, s96
	s_or_b32 s23, s96, 0x200
	v_cmp_le_u32_e64 s[20:21], s23, v2
	v_cmp_le_u32_e64 s[98:99], s23, v5
	s_bcnt1_i32_b64 s24, s[20:21]
	s_bcnt1_i32_b64 s25, s[98:99]
	s_add_i32 s24, s24, s25
	s_cmp_gt_u32 s24, 12
	s_cselect_b32 s96, s23, s96
	s_or_b32 s23, s96, 0x100
	v_cmp_le_u32_e64 s[20:21], s23, v2
	v_cmp_le_u32_e64 s[98:99], s23, v5
	s_bcnt1_i32_b64 s24, s[20:21]
	s_bcnt1_i32_b64 s25, s[98:99]
	s_add_i32 s24, s24, s25
	s_cmp_gt_u32 s24, 12
	s_cselect_b32 s96, s23, s96
	s_or_b32 s23, s96, 0x80
	v_cmp_le_u32_e64 s[20:21], s23, v2
	v_cmp_le_u32_e64 s[98:99], s23, v5
	s_bcnt1_i32_b64 s24, s[20:21]
	s_bcnt1_i32_b64 s25, s[98:99]
	s_add_i32 s24, s24, s25
	s_cmp_gt_u32 s24, 12
	s_cselect_b32 s96, s23, s96
	s_or_b32 s23, s96, 64
	v_cmp_le_u32_e64 s[20:21], s23, v2
	v_cmp_le_u32_e64 s[98:99], s23, v5
	s_bcnt1_i32_b64 s24, s[20:21]
	s_bcnt1_i32_b64 s25, s[98:99]
	s_add_i32 s24, s24, s25
	s_cmp_gt_u32 s24, 12
	s_cselect_b32 s96, s23, s96
	s_or_b32 s23, s96, 32
	v_cmp_le_u32_e64 s[20:21], s23, v2
	v_cmp_le_u32_e64 s[98:99], s23, v5
	s_bcnt1_i32_b64 s24, s[20:21]
	s_bcnt1_i32_b64 s25, s[98:99]
	s_add_i32 s24, s24, s25
	s_cmp_gt_u32 s24, 12
	s_cselect_b32 s96, s23, s96
	s_or_b32 s23, s96, 16
	v_cmp_le_u32_e64 s[20:21], s23, v2
	v_cmp_le_u32_e64 s[98:99], s23, v5
	s_bcnt1_i32_b64 s24, s[20:21]
	s_bcnt1_i32_b64 s25, s[98:99]
	s_add_i32 s24, s24, s25
	s_cmp_gt_u32 s24, 12
	s_cselect_b32 s96, s23, s96
	s_or_b32 s23, s96, 8
	v_cmp_le_u32_e64 s[20:21], s23, v2
	v_cmp_le_u32_e64 s[98:99], s23, v5
	s_bcnt1_i32_b64 s24, s[20:21]
	s_bcnt1_i32_b64 s25, s[98:99]
	s_add_i32 s24, s24, s25
	s_cmp_gt_u32 s24, 12
	s_cselect_b32 s96, s23, s96
	s_or_b32 s23, s96, 4
	v_cmp_le_u32_e64 s[20:21], s23, v2
	v_cmp_le_u32_e64 s[98:99], s23, v5
	s_bcnt1_i32_b64 s24, s[20:21]
	s_bcnt1_i32_b64 s25, s[98:99]
	s_add_i32 s24, s24, s25
	s_cmp_gt_u32 s24, 12
	s_cselect_b32 s96, s23, s96
	s_or_b32 s23, s96, 2
	v_cmp_le_u32_e64 s[20:21], s23, v2
	v_cmp_le_u32_e64 s[98:99], s23, v5
	s_bcnt1_i32_b64 s24, s[20:21]
	s_bcnt1_i32_b64 s25, s[98:99]
	s_add_i32 s24, s24, s25
	s_cmp_gt_u32 s24, 12
	s_cselect_b32 s96, s23, s96
	s_or_b32 s23, s96, 1
	v_cmp_le_u32_e64 s[20:21], s23, v2
	v_cmp_le_u32_e64 s[98:99], s23, v5
	s_bcnt1_i32_b64 s24, s[20:21]
	s_bcnt1_i32_b64 s25, s[98:99]
	s_add_i32 s24, s24, s25
	s_cmp_gt_u32 s24, 12
	s_cselect_b32 s96, s23, s96
.Ltk_join:
	s_mov_b32 s22, -1
	v_cmp_lt_u32_e64 s[20:21], s96, v2
	s_and_b64 s[80:81], s[70:71], s[20:21]
	v_cmp_lt_u32_e64 s[20:21], s96, v5
	s_and_b64 s[78:79], vcc, s[20:21]
	v_cmp_lt_u32_e64 s[20:21], s96, v4
	s_and_b64 s[76:77], s[16:17], s[20:21]
	v_cmp_lt_u32_e64 s[20:21], s96, v0
	s_and_b64 s[74:75], s[18:19], s[20:21]
	s_ashr_i32 s21, s95, 31
	s_add_u32 s20, s95, s26
	s_addc_u32 s21, s21, 0
	s_lshl_b64 s[20:21], s[20:21], 7
	v_cndmask_b32_e64 v3, 0, 1, s[80:81]
	v_cndmask_b32_e64 v8, 0, 1, s[78:79]
	v_cndmask_b32_e64 v7, 0, 1, s[76:77]
	v_cndmask_b32_e64 v6, 0, 1, s[74:75]
	s_add_u32 s72, s92, s20
	v_cmp_ne_u32_e64 s[22:23], 0, v3
	v_cmp_ne_u32_e64 s[24:25], 0, v8
	v_cmp_ne_u32_e64 s[38:39], 0, v7
	v_cmp_ne_u32_e64 s[40:41], 0, v6
	s_addc_u32 s73, s93, s21
	s_and_saveexec_b64 s[20:21], s[8:9]
	s_cbranch_execz .LBB0_436
	v_mov_b32_e32 v11, s94
	v_mov_b32_e32 v12, s91
	v_mov_b32_e32 v10, v1
	global_store_dwordx3 v1, v[10:12], s[72:73]
